# baseline (speedup 1.0000x reference)
.LBB0_296:
	s_or_b64 exec, exec, s[0:1]
	s_bfe_u32 s98, s70, 0x30003
	s_cmp_eq_u32 s98, 0
	s_cbranch_scc1 .Lsg_done0
.Lsg_loop0:
	s_sleep 6
	s_sub_u32 s98, s98, 1
	s_cmp_lg_u32 s98, 0
	s_cbranch_scc1 .Lsg_loop0
.Lsg_done0:
	s_add_u32 s0, s60, 0xbe00000
	s_addc_u32 s1, s61, 0
	v_writelane_b32 v252, s0, 36
	s_cmpk_lt_i32 s62, 0x80
	s_waitcnt lgkmcnt(0)
	v_writelane_b32 v252, s1, 37
	s_cselect_b64 s[0:1], -1, 0
	s_cmp_lt_i32 s70, 64
	s_cselect_b64 s[4:5], -1, 0
	s_or_b64 s[2:3], s[4:5], s[0:1]
	s_and_b64 vcc, exec, s[2:3]
	s_barrier
	s_cbranch_vccz .LBB0_321
	v_mov_b32_e32 v144, v218
	s_andn2_b64 vcc, exec, s[4:5]
	v_readfirstlane_b32 s19, v144
	s_cbranch_vccnz .LBB0_321
	s_ashr_i32 s2, s70, 31
	s_lshr_b32 s2, s2, 29
	s_add_i32 s2, s70, s2
	s_and_b32 s3, s2, -8
	s_sub_i32 s6, s70, s3
	s_cmp_gt_i32 s6, -1
	s_cbranch_scc0 .LBB0_300
	s_lshl_b32 s3, s6, 3
	s_cbranch_execz .LBB0_301
	s_branch .LBB0_302

.Lsg_done1:
	s_add_u32 s0, s60, 0x1d800000
	s_addc_u32 s1, s61, 0
	v_writelane_b32 v252, s0, 44
	v_mov_b32_e32 v158, v218
	s_waitcnt lgkmcnt(0)
	v_writelane_b32 v252, s1, 45
	s_add_u32 s0, s60, 0x1e800000
	s_addc_u32 s1, s61, 0
	v_writelane_b32 v252, s0, 46
	s_cmpk_lt_i32 s70, 0x100
	s_barrier
	v_writelane_b32 v252, s1, 47
	s_cselect_b64 s[0:1], -1, 0
	v_writelane_b32 v252, s0, 48
	s_cmpk_gt_i32 s70, 0xff
	v_readfirstlane_b32 s6, v158
	v_writelane_b32 v252, s1, 49
	s_cbranch_scc1 .LBB0_490
	s_add_u32 s22, s60, 0x1d00000
	s_addc_u32 s23, s61, 0
	s_and_b32 s2, s70, 7
	s_bfe_u32 s3, s70, 0x20003
	s_cmpk_gt_u32 s70, 0x7f
	s_cbranch_scc0 .LBB0_464
	s_lshl_b32 s1, s3, 10
	s_lshl_b32 s4, s2, 20
	s_bfe_u32 s0, s70, 0x20005
	s_or_b32 s4, s1, s4
	s_add_u32 s16, s28, s4
	s_addc_u32 s17, s29, 0
	s_lshl_b32 s4, s0, 20
	s_or_b32 s1, s4, s1
	s_add_u32 s18, s78, s1
	s_addc_u32 s19, s79, 0
	s_lshl_b32 s0, s0, 3
	s_or_b32 s42, s0, s2
	s_cbranch_execz .LBB0_465
	s_mov_b32 s2, s3
	s_branch .LBB0_466

.Lsg_done2:
	v_mov_b32_e32 v220, v218
	s_cmpk_lt_i32 s70, 0x200
	s_waitcnt lgkmcnt(0)
	s_barrier
	s_cselect_b64 s[10:11], -1, 0
	s_cmpk_gt_i32 s70, 0x1ff
	v_readfirstlane_b32 s12, v220
	s_cbranch_scc1 .LBB0_604
	s_ashr_i32 s0, s70, 31
	s_lshr_b32 s0, s0, 29
	s_add_i32 s2, s70, s0
	s_and_b32 s0, s2, -8
	s_sub_i32 s3, s70, s0
	s_cmp_gt_i32 s3, -1
	s_cbranch_scc0 .LBB0_605
	s_lshl_b32 s4, s3, 6
	s_cbranch_execz .LBB0_606
	s_branch .LBB0_607

.Lsg_done3:
	v_readlane_b32 s0, v252, 48
	s_add_u32 s10, s60, 0x11000000
	v_readlane_b32 s1, v252, 49
	s_addc_u32 s11, s61, 0
	s_and_b64 vcc, exec, s[0:1]
	s_waitcnt lgkmcnt(0)
	s_barrier
	s_cbranch_vccz .LBB0_842
	v_mov_b32_e32 v140, v218
	s_mov_b32 s0, 0
	s_cmp_gt_i32 s0, 0
	v_readfirstlane_b32 s16, v140
	s_cbranch_scc1 .LBB0_842
	v_lshlrev_b32_e32 v0, 4, v140
	v_add_u32_e32 v1, 0x2000, v0
	v_ashrrev_i32_e32 v2, 31, v1
	v_lshrrev_b32_e32 v2, 22, v2
	v_add_u32_e32 v2, v1, v2
	v_ashrrev_i32_e32 v8, 10, v2
	v_mul_i32_i24_e32 v2, 0x400, v8
	v_sub_u32_e32 v1, v1, v2
	v_lshrrev_b32_e32 v2, 4, v1
	v_bitop3_b32 v1, v2, v1, 32 bitop3:0x6c
	v_ashrrev_i32_e32 v2, 31, v1
	v_lshrrev_b32_e32 v2, 26, v2
	v_add_u32_e32 v2, v1, v2
	v_lshlrev_b32_e32 v3, 3, v8
	v_ashrrev_i32_e32 v9, 6, v2
	v_and_b32_e32 v3, -16, v3
	v_add_u32_e32 v3, v9, v3
	v_and_b32_e32 v4, 3, v9
	s_mov_b32 s0, 0xfffe0
	v_lshrrev_b32_e32 v5, 2, v3
	v_lshlrev_b32_e32 v6, 1, v3
	v_and_b32_e32 v2, 0xc0, v2
	v_and_or_b32 v4, v3, s0, v4
	v_and_b32_e32 v5, 4, v5
	v_and_b32_e32 v6, 24, v6
	v_sub_u32_e32 v1, v1, v2
	v_mov_b32_e32 v2, 1
	v_or3_b32 v4, v4, v5, v6
	v_lshlrev_b32_e32 v5, 5, v8
	v_ashrrev_i16_sdwa v1, v2, sext(v1) dst_sel:DWORD dst_unused:UNUSED_PAD src0_sel:DWORD src1_sel:BYTE_0
	v_and_b32_e32 v5, 32, v5
	v_bfe_i32 v10, v1, 0, 16
	v_add_lshl_u32 v1, v5, v10, 1
	v_lshl_add_u32 v128, v4, 12, v1
	v_lshl_add_u32 v130, v3, 12, v1
	v_bfe_i32 v1, v140, 27, 1
	v_lshrrev_b32_e32 v1, 22, v1
	v_add_u32_e32 v1, v0, v1
	v_and_b32_e32 v1, 0xfffffc00, v1
	v_sub_u32_e32 v0, v0, v1
	v_lshrrev_b32_e32 v1, 4, v0
	v_ashrrev_i32_e32 v3, 31, v140
	v_bitop3_b32 v0, v1, v0, 32 bitop3:0x6c
	v_lshrrev_b32_e32 v3, 26, v3
	v_ashrrev_i32_e32 v1, 31, v0
	v_add_u32_e32 v3, v140, v3
	v_lshrrev_b32_e32 v1, 26, v1
	v_ashrrev_i32_e32 v12, 6, v3
	v_add_u32_e32 v1, v0, v1
	v_lshlrev_b32_e32 v3, 3, v12
	v_ashrrev_i32_e32 v11, 6, v1
	v_and_b32_e32 v3, -16, v3
	v_add_u32_e32 v3, v11, v3
	v_and_b32_e32 v4, 3, v11
	v_and_or_b32 v4, v3, s0, v4
	s_and_b32 s98, s70, 7
	s_lshl_b32 s98, s98, 5
	s_lshr_b32 s99, s70, 3
	s_or_b32 s98, s98, s99
	s_ashr_i32 s0, s98, 2
	s_ashr_i32 s15, s16, 6
	s_ashr_i32 s1, s0, 31
	s_ashr_i32 s14, s16, 8
	s_lshl_b32 s20, s15, 10
	s_lshl_b64 s[18:19], s[0:1], 20
	v_readlane_b32 s2, v252, 38
	v_readlane_b32 s3, v252, 39
	s_add_u32 s4, s2, s18
	s_addc_u32 s5, s3, s19
	s_lshl_b32 s1, s0, 6
	s_and_b32 s21, s1, 0xfffffc00
	s_lshl_b32 s1, s98, 8
	s_and_b32 s2, s1, 0x300
	v_lshrrev_b32_e32 v5, 2, v3
	v_lshlrev_b32_e32 v6, 1, v3
	v_and_b32_e32 v1, 0xc0, v1
	s_or_b32 s6, s21, s2
	v_and_b32_e32 v5, 4, v5
	v_and_b32_e32 v6, 24, v6
	v_sub_u32_e32 v0, v0, v1
	s_ashr_i32 s7, s6, 31
	v_or3_b32 v4, v4, v5, v6
	v_lshlrev_b32_e32 v5, 5, v12
	v_ashrrev_i16_sdwa v0, v2, sext(v0) dst_sel:DWORD dst_unused:UNUSED_PAD src0_sel:DWORD src1_sel:BYTE_0
	s_lshl_b64 s[6:7], s[6:7], 12
	v_readlane_b32 s12, v252, 44
	v_and_b32_e32 v5, 32, v5
	v_bfe_i32 v13, v0, 0, 16
	v_readlane_b32 s13, v252, 45
	s_add_u32 s6, s12, s6
	v_add_lshl_u32 v0, v5, v13, 1
	s_addc_u32 s7, s13, s7
	s_add_i32 s3, s20, 0
	v_lshl_add_u32 v132, v4, 12, v0
	s_add_i32 m0, s3, 0x10000
	v_lshl_add_u32 v134, v3, 12, v0
	global_load_lds_dwordx4 v132, s[6:7]
	s_add_i32 m0, s3, 0x12000
	s_add_u32 s12, s6, 0x80000
	global_load_lds_dwordx4 v128, s[6:7]
	s_addc_u32 s13, s7, 0
	s_add_i32 m0, s3, 0x14000
	s_add_i32 s27, s3, 0x2000
	global_load_lds_dwordx4 v132, s[12:13]
	s_add_i32 m0, s3, 0x16000
	v_mov_b32_e32 v133, 0
	global_load_lds_dwordx4 v128, s[12:13]
	s_mov_b32 m0, s3
	s_add_u32 s12, s4, 0x80000
	global_load_lds_dwordx4 v134, s[4:5]
	s_mov_b32 m0, s27
	s_addc_u32 s13, s5, 0
	s_add_i32 s28, s3, 0x4000
	global_load_lds_dwordx4 v130, s[4:5]
	s_mov_b32 m0, s28
	s_add_i32 s29, s3, 0x6000
	global_load_lds_dwordx4 v134, s[12:13]
	s_mov_b32 m0, s29
	v_mov_b32_e32 v129, v133
	global_load_lds_dwordx4 v130, s[12:13]
	v_mov_b32_e32 v135, v133
	v_mov_b32_e32 v131, v133
	s_cmp_eq_u32 s14, 1
	v_lshl_add_u64 v[6:7], s[6:7], 0, v[132:133]
	v_lshl_add_u64 v[4:5], s[6:7], 0, v[128:129]
	v_lshl_add_u64 v[0:1], s[4:5], 0, v[134:135]
	s_cselect_b64 s[12:13], -1, 0
	s_cmp_lg_u32 s14, 1
	v_lshl_add_u64 v[2:3], s[4:5], 0, v[130:131]
	s_cbranch_scc1 .LBB0_797
	s_barrier

.Lsg_done4:
	v_mov_b32_e32 v182, v218
	s_waitcnt lgkmcnt(0)
	s_barrier
	s_and_b64 vcc, exec, s[8:9]
	v_readfirstlane_b32 s16, v182
	s_cbranch_vccnz .LBB0_897
	s_ashr_i32 s0, s70, 31
	s_lshr_b32 s0, s0, 29
	s_add_i32 s2, s70, s0
	s_and_b32 s0, s2, -8
	s_sub_i32 s3, s70, s0
	s_cmp_gt_i32 s3, -1
	s_cbranch_scc0 .LBB0_898
	s_lshl_b32 s4, s3, 6
	s_cbranch_execz .LBB0_899
	s_branch .LBB0_900

.Lsg_done5:
	s_add_u32 s10, s60, 0x10000000
	s_addc_u32 s11, s61, 0
	v_mov_b32_e32 v144, v218
	s_waitcnt lgkmcnt(0)
	s_barrier
	s_cmpk_gt_i32 s70, 0x7ff
	v_readfirstlane_b32 s15, v144
	s_cbranch_scc1 .LBB0_1012
	s_ashr_i32 s0, s70, 31
	s_lshr_b32 s0, s0, 29
	s_add_i32 s3, s70, s0
	s_and_b32 s0, s3, -8
	s_sub_i32 s2, s70, s0
	s_cmp_gt_i32 s2, -1
	s_cbranch_scc0 .LBB0_991
	s_lshl_b32 s4, s2, 8
	s_cbranch_execz .LBB0_992
	s_branch .LBB0_993

.Lsg_done6:
	v_mov_b32_e32 v154, v218
	s_waitcnt lgkmcnt(0)
	s_barrier
	s_and_b64 vcc, exec, s[8:9]
	v_readfirstlane_b32 s7, v154
	s_cbranch_vccnz .LBB0_1088
	s_ashr_i32 s0, s70, 31
	s_lshr_b32 s0, s0, 29
	s_add_i32 s4, s70, s0
	s_and_b32 s0, s4, -8
	s_sub_i32 s2, s70, s0
	s_cmp_gt_i32 s2, -1
	s_cbranch_scc0 .LBB0_1067
	s_lshl_b32 s3, s2, 6
	s_ashr_i32 s0, s4, 3
	s_cbranch_execz .LBB0_1068
	s_branch .LBB0_1069

.Lsg_done7:
	s_waitcnt lgkmcnt(0)
	s_barrier
	s_nop 0
	v_readfirstlane_b32 s0, v218
	s_ashr_i32 s6, s0, 6
	s_add_i32 s0, s6, s69
	s_cmpk_gt_i32 s0, 0x3fff
	s_cbranch_scc1 .LBB0_1171
	v_and_b32_e32 v40, 63, v218
	v_lshlrev_b32_e32 v32, 5, v40
	v_mov_b32_e32 v33, 0
	v_lshl_add_u64 v[0:1], s[56:57], 0, v[32:33]
	s_mov_b64 s[0:1], 0x1800
	v_lshl_add_u64 v[34:35], v[0:1], 0, s[0:1]
	v_add_co_u32_e32 v36, vcc, 0x1000, v0
	s_mov_b64 s[0:1], 0x1000
	s_nop 0
	v_addc_co_u32_e32 v37, vcc, 0, v1, vcc
	v_lshl_add_u64 v[38:39], v[0:1], 0, s[0:1]
	global_load_dwordx4 v[0:3], v[34:35], off offset:16
	global_load_dwordx4 v[4:7], v[36:37], off
	global_load_dwordx4 v[8:11], v[36:37], off offset:2048
	global_load_dwordx4 v[12:15], v[38:39], off offset:16
	global_load_dwordx4 v[16:19], v32, s[56:57] offset:2064
	global_load_dwordx4 v[20:23], v32, s[56:57] offset:2048
	global_load_dwordx4 v[24:27], v32, s[56:57] offset:16
	global_load_dwordx4 v[28:31], v32, s[56:57]
	v_mbcnt_hi_u32_b32 v36, -1, v219
	v_and_b32_e32 v37, 64, v36
	v_add_u32_e32 v37, 64, v37
	v_xor_b32_e32 v38, 1, v36
	v_cmp_lt_i32_e32 vcc, v38, v37
	s_lshl_b32 s0, s62, 6
	s_ashr_i32 s1, s6, 31
	v_cndmask_b32_e32 v38, v36, v38, vcc
	v_lshlrev_b32_e32 v168, 2, v38
	v_xor_b32_e32 v38, 2, v36
	v_cmp_lt_i32_e32 vcc, v38, v37
	s_ashr_i32 s2, s69, 31
	s_add_u32 s4, s6, s69
	v_cndmask_b32_e32 v38, v36, v38, vcc
	v_lshlrev_b32_e32 v169, 2, v38
	v_xor_b32_e32 v38, 4, v36
	v_cmp_lt_i32_e32 vcc, v38, v37
	s_addc_u32 s5, s1, s2
	s_lshl_b64 s[2:3], s[4:5], 13
	v_cndmask_b32_e32 v38, v36, v38, vcc
	v_lshlrev_b32_e32 v170, 2, v38
	v_xor_b32_e32 v38, 8, v36
	v_cmp_lt_i32_e32 vcc, v38, v37
	s_add_u32 s2, s58, s2
	s_mul_i32 s7, s62, 56
	v_cndmask_b32_e32 v38, v36, v38, vcc
	s_addc_u32 s3, s59, s3
	s_add_i32 s37, s6, s7
	s_mul_i32 s7, s62, 48
	v_mov_b32_e32 v35, v33
	v_lshl_add_u64 v[162:163], s[58:59], 0, v[32:33]
	v_lshlrev_b32_e32 v171, 2, v38
	v_xor_b32_e32 v38, 16, v36
	v_lshl_add_u64 v[32:33], s[2:3], 0, v[32:33]
	s_mov_b64 s[2:3], 0x1810
	s_ashr_i32 s1, s0, 31
	s_add_i32 s38, s6, s7
	s_mul_i32 s7, s62, 40
	v_cmp_lt_i32_e32 vcc, v38, v37
	v_lshl_add_u64 v[164:165], v[32:33], 0, s[2:3]
	s_lshl_b64 s[2:3], s[0:1], 13
	s_add_i32 s36, s6, s68
	s_add_i32 s39, s6, s7
	s_lshl_b64 s[4:5], s[4:5], 12
	v_cndmask_b32_e32 v38, v36, v38, vcc
	s_add_u32 s4, s60, s4
	v_lshlrev_b32_e32 v34, 4, v40
	v_lshlrev_b32_e32 v172, 2, v38
	v_xor_b32_e32 v38, 32, v36
	s_addc_u32 s5, s61, s5
	v_cmp_lt_i32_e32 vcc, v38, v37
	v_lshl_add_u64 v[32:33], s[4:5], 0, v[34:35]
	s_mov_b64 s[4:5], 0xbe00800
	s_mul_i32 s7, s62, 24
	v_cndmask_b32_e32 v36, v36, v38, vcc
	v_lshl_add_u64 v[166:167], v[32:33], 0, s[4:5]
	s_lshl_b64 s[4:5], s[0:1], 12
	s_lshl_b32 s1, s62, 5
	s_add_i32 s40, s6, s7
	s_lshl_b32 s7, s62, 4
	s_movk_i32 s33, 0x1000
	v_lshl_add_u64 v[160:161], s[76:77], 0, v[34:35]
	v_lshlrev_b32_e32 v173, 2, v36
	s_add_i32 s1, s6, s1
	s_add_i32 s41, s6, s7
	v_mov_b32_e32 v174, 0x358637bd
	s_mov_b32 s42, 0x800000
	s_movk_i32 s43, 0xf000
	s_branch .LBB0_1143
